# v6 + phase-0 x copy with four 16-byte loads in flight per lane
# baseline (speedup 1.0000x reference)
; __device__ __forceinline__ unsigned pk2(float lo, float hi) { f32x2_t v = {lo, hi}; bf16x2_t b = __builtin_convertvector(v, bf16x2_t); return __builtin_bit_cast(unsigned, b); }
; __device__ __forceinline__ void xinit_phase(const P& p, size_t i0, size_t stride) {
;     const size_t n = (size_t)MROWS * D / 4;
;     for (size_t i = i0; i < n; i += stride) {
;         const size_t e = i * 4;
;         const float4 v = e < (size_t)NPROMPT * D ? *(const float4*)(p.in[0] + e) : *(const float4*)(p.in[1] + (e - (size_t)NPROMPT * D));
;         *(float4*)(p.X + e) = v;
;         *(uint2*)(p.Xb + e) = make_uint2(pk2(v.x, v.y), pk2(v.z, v.w));
;     }
; }
.LBB0_47:
	s_ashr_i32 s31, s30, 31
	s_lshl_b64 s[4:5], s[30:31], 9
	v_lshl_add_u64 v[4:5], s[4:5], 0, v[2:3]
	s_mov_b64 s[4:5], 0x410000
	v_cmp_gt_u64_e32 vcc, s[4:5], v[4:5]
	s_and_saveexec_b64 s[4:5], vcc
	v_readlane_b32 s20, v249, 60
	v_readlane_b32 s21, v249, 61
	s_cbranch_execz .LBB0_50
	s_add_u32 s8, s58, 0xfc000000
	s_addc_u32 s9, s59, -1
	s_lshl_b64 s[10:11], s[30:31], 13
	s_load_dwordx16 s[36:51], s[0:1], 0xc0
	v_lshl_add_u64 v[6:7], v[2:3], 4, s[10:11]
	s_lshl_b64 s[10:11], s[28:29], 13
	s_lshl_b64 s[12:13], s[30:31], 12
	s_add_u32 s12, s82, s12
	s_addc_u32 s13, s83, s13
	v_lshl_add_u64 v[8:9], v[2:3], 3, s[12:13]
	s_lshl_b64 s[12:13], s[28:29], 12
	s_waitcnt lgkmcnt(0)
	s_add_u32 s14, s42, 8
	v_lshl_add_u64 v[8:9], v[8:9], 0, 4
	s_addc_u32 s15, s43, 0
	s_mov_b64 s[16:17], 0
	v_mov_b64_e32 v[10:11], v[4:5]
	s_cmp_eq_u32 s20, 0x20000
	s_cbranch_scc0 .LBB0_49
	s_cmp_eq_u32 s21, 0
	s_cbranch_scc0 .LBB0_49
	s_sub_u32 s18, s14, s56
	s_subb_u32 s19, s15, s57
	s_mov_b32 s100, 8
.Lxinit_pre:
	v_lshl_add_u64 v[18:19], s[56:57], 0, v[6:7]
	v_lshl_add_u64 v[20:21], v[18:19], 0, s[10:11]
	v_lshl_add_u64 v[22:23], v[20:21], 0, s[10:11]
	v_lshl_add_u64 v[24:25], v[22:23], 0, s[10:11]
	global_load_dwordx4 v[26:29], v[18:19], off
	global_load_dwordx4 v[30:33], v[20:21], off
	global_load_dwordx4 v[34:37], v[22:23], off
	global_load_dwordx4 v[38:41], v[24:25], off
	v_lshl_add_u64 v[18:19], v[18:19], 0, s[18:19]
	v_lshl_add_u64 v[20:21], v[20:21], 0, s[18:19]
	v_lshl_add_u64 v[22:23], v[22:23], 0, s[18:19]
	v_lshl_add_u64 v[24:25], v[24:25], 0, s[18:19]
	v_lshl_add_u64 v[42:43], v[8:9], 0, s[12:13]
	v_lshl_add_u64 v[44:45], v[42:43], 0, s[12:13]
	v_lshl_add_u64 v[46:47], v[44:45], 0, s[12:13]
	v_lshl_add_u64 v[6:7], s[10:11], 2, v[6:7]
	v_lshl_add_u64 v[10:11], s[20:21], 2, v[10:11]
	s_waitcnt vmcnt(3)
	global_store_dwordx4 v[18:19], v[26:29], off offset:-8
	v_cvt_pk_bf16_f32 v48, v26, v27
	v_cvt_pk_bf16_f32 v49, v28, v29
	global_store_dwordx2 v[8:9], v[48:49], off offset:-4
	v_lshl_add_u64 v[8:9], s[12:13], 2, v[8:9]
	s_waitcnt vmcnt(4)
	global_store_dwordx4 v[20:21], v[30:33], off offset:-8
	v_cvt_pk_bf16_f32 v50, v30, v31
	v_cvt_pk_bf16_f32 v51, v32, v33
	global_store_dwordx2 v[42:43], v[50:51], off offset:-4
	s_waitcnt vmcnt(5)
	global_store_dwordx4 v[22:23], v[34:37], off offset:-8
	v_cvt_pk_bf16_f32 v52, v34, v35
	v_cvt_pk_bf16_f32 v53, v36, v37
	global_store_dwordx2 v[44:45], v[52:53], off offset:-4
	s_waitcnt vmcnt(6)
	global_store_dwordx4 v[24:25], v[38:41], off offset:-8
	v_cvt_pk_bf16_f32 v54, v38, v39
	v_cvt_pk_bf16_f32 v55, v40, v41
	global_store_dwordx2 v[46:47], v[54:55], off offset:-4
	s_sub_u32 s100, s100, 1
	s_cmp_lg_u32 s100, 0
	s_cbranch_scc1 .Lxinit_pre
	s_mov_b64 s[18:19], 0x40ffff
	v_cmp_lt_u64_e32 vcc, s[18:19], v[10:11]
	s_nop 1
	s_mov_b64 s[16:17], vcc
	s_andn2_b64 exec, exec, vcc
	s_cbranch_execz .LBB0_50
